# attention task prologue: dropped the join wait that made wave 0 sit out one load latency before issuing its Q/K/V loads (on top of v95)
# speedup vs baseline: 1.0109x; 1.0107x over previous
.LBB0_503:
	s_or_b64 exec, exec, s[54:55]
	s_lshl_b32 s3, s98, 5
	s_ashr_i32 s54, s3, 31
	s_add_u32 s12, s3, s12
	v_and_b32_e32 v186, 31, v154
	s_addc_u32 s54, s54, 0
	v_or_b32_e32 v156, s12, v186
	v_mov_b32_e32 v157, s54
	s_add_u32 s54, s85, s57
	v_lshlrev_b64 v[2:3], 14, v[156:157]
	v_lshrrev_b32_e32 v121, 5, v185
	s_addc_u32 s55, s86, 0
	s_add_i32 s33, s33, -16
	v_lshl_add_u64 v[2:3], s[10:11], 0, v[2:3]
	s_add_u32 vcc_lo, s10, s14
	v_lshlrev_b32_e32 v187, 4, v154
	v_lshl_add_u64 v[2:3], v[2:3], 0, s[14:15]
	v_lshlrev_b32_e32 v162, 4, v121
	v_mov_b32_e32 v163, v129
	s_addc_u32 vcc_hi, s11, 0
	v_and_b32_e32 v128, 0xf0, v187
	v_lshl_add_u64 v[2:3], v[2:3], 0, v[162:163]
	v_lshl_add_u64 v[160:161], vcc, 0, v[128:129]
	v_ashrrev_i32_e32 v119, 4, v154
	v_lshl_add_u64 v[52:53], v[2:3], 0, s[36:37]
	v_add_co_u32_e32 v2, vcc, s65, v2
	v_add_u32_e32 v1, s56, v119
	s_nop 0
	v_addc_co_u32_e32 v3, vcc, 0, v3, vcc
	v_mov_b32_e32 v6, s33
	v_cmp_lt_i32_e32 vcc, 15, v1
	v_min_i32_e32 v0, 0x80f, v1
	global_load_dwordx4 v[80:83], v[2:3], off
	global_load_dwordx4 v[86:89], v[52:53], off offset:224
	v_cndmask_b32_e32 v1, v179, v6, vcc
	v_add_u32_e32 v2, v1, v0
	v_ashrrev_i32_e32 v3, 31, v2
	v_lshlrev_b64 v[2:3], 14, v[2:3]
	v_lshl_add_u64 v[2:3], v[160:161], 0, v[2:3]
	v_add_co_u32_e32 v4, vcc, s65, v2
	v_ashrrev_i32_e32 v1, 31, v0
	s_nop 0
	v_addc_co_u32_e32 v5, vcc, 0, v3, vcc
	v_add_co_u32_e32 v2, vcc, s63, v2
	v_lshl_add_u64 v[0:1], v[0:1], 2, s[54:55]
	s_nop 0
	v_addc_co_u32_e32 v3, vcc, 0, v3, vcc
	global_load_dwordx4 v[96:99], v[52:53], off offset:160
	global_load_dwordx4 v[100:103], v[52:53], off offset:192
	global_load_dwordx4 v[12:15], v[4:5], off offset:2048
	global_load_dwordx4 v[8:11], v[2:3], off
	v_add_u32_e32 v2, 0x200, v154
	v_ashrrev_i32_e32 v189, 4, v2
	v_add_u32_e32 v3, s56, v189
	v_cmp_lt_i32_e32 vcc, 15, v3
	v_min_i32_e32 v2, 0x80f, v3
	v_mul_lo_u32 v48, v48, s66
	v_cndmask_b32_e32 v3, v179, v6, vcc
	v_add_u32_e32 v4, v3, v2
	v_ashrrev_i32_e32 v5, 31, v4
	v_lshlrev_b64 v[4:5], 14, v[4:5]
	v_lshl_add_u64 v[54:55], v[160:161], 0, v[4:5]
	v_add_co_u32_e32 v4, vcc, s65, v54
	v_ashrrev_i32_e32 v3, 31, v2
	s_nop 0
	v_addc_co_u32_e32 v5, vcc, 0, v55, vcc
	global_load_dword v120, v[0:1], off
	s_nop 0
	global_load_dwordx4 v[4:7], v[4:5], off offset:2048
	v_add_co_u32_e32 v0, vcc, s63, v54
	v_add3_u32 v48, s67, v48, v50
	s_nop 0
	v_addc_co_u32_e32 v1, vcc, 0, v55, vcc
	v_lshl_add_u64 v[54:55], v[2:3], 2, s[54:55]
	global_load_dwordx4 v[0:3], v[0:1], off
	s_nop 0
	global_load_dword v118, v[54:55], off
	global_load_dwordx4 v[172:175], v[52:53], off offset:32
	global_load_dwordx4 v[164:167], v[52:53], off offset:64
	global_load_dwordx4 v[148:151], v[52:53], off offset:96
	global_load_dwordx4 v[140:143], v[52:53], off offset:128
	s_waitcnt vmcnt(19)
	ds_write2_b64 v48, v[36:37], v[38:39] offset1:1
	ds_write2_b64 v48, v[32:33], v[34:35] offset0:2 offset1:3
	ds_write2_b64 v48, v[24:25], v[26:27] offset0:4 offset1:5
	s_waitcnt vmcnt(15)
	ds_write2_b64 v48, v[44:45], v[46:47] offset0:6 offset1:7
	s_waitcnt vmcnt(14)
	ds_write2_b64 v48, v[40:41], v[42:43] offset0:8 offset1:9
	ds_write2_b64 v48, v[28:29], v[30:31] offset0:10 offset1:11
	ds_write2_b64 v48, v[20:21], v[22:23] offset0:12 offset1:13
	ds_write2_b64 v48, v[16:17], v[18:19] offset0:14 offset1:15
	v_and_b32_e32 v16, 32, v185
	v_add_u32_e32 v16, 0, v16
	v_add_u32_e32 v16, 0x25e00, v16
	ds_read_b128 v[76:79], v16
	ds_read_b128 v[72:75], v16 offset:16
	ds_read_b128 v[68:71], v16 offset:64
	ds_read_b128 v[64:67], v16 offset:80
	ds_read_b128 v[60:63], v16 offset:128
	ds_read_b128 v[56:59], v16 offset:144
	ds_read_b128 v[52:55], v16 offset:192
	ds_read_b128 v[48:51], v16 offset:208
	ds_read_b128 v[44:47], v16 offset:256
	ds_read_b128 v[40:43], v16 offset:272
	ds_read_b128 v[36:39], v16 offset:320
	ds_read_b128 v[32:35], v16 offset:336
	ds_read_b128 v[28:31], v16 offset:384
	ds_read_b128 v[24:27], v16 offset:400
	ds_read_b128 v[20:23], v16 offset:448
	ds_read_b128 v[16:19], v16 offset:464
	s_waitcnt vmcnt(13)
	v_and_b32_e32 v177, 0xffff0000, v80
	s_waitcnt vmcnt(12)
	v_and_b32_e32 v85, 0xffff0000, v89
	v_lshlrev_b32_e32 v122, 16, v89
	v_lshlrev_b32_e32 v110, 16, v88
	v_and_b32_e32 v89, 0xffff0000, v88
	v_mov_b32_e32 v88, v85
	v_and_b32_e32 v93, 0xffff0000, v87
	v_mov_b32_e32 v123, v110
	v_pk_mul_f32 v[90:91], v[88:89], v[88:89]
	v_lshlrev_b32_e32 v124, 16, v87
	v_lshlrev_b32_e32 v108, 16, v86
	v_and_b32_e32 v87, 0xffff0000, v86
	v_mov_b32_e32 v86, v93
	v_pk_fma_f32 v[190:191], v[122:123], v[122:123], v[90:91]
	v_mov_b32_e32 v125, v108
	v_pk_mul_f32 v[90:91], v[86:87], v[86:87]
	s_waitcnt vmcnt(10)
	v_and_b32_e32 v131, 0xffff0000, v101
	v_pk_fma_f32 v[192:193], v[124:125], v[124:125], v[90:91]
	v_and_b32_e32 v91, 0xffff0000, v103
	v_lshlrev_b32_e32 v106, 16, v102
	v_and_b32_e32 v95, 0xffff0000, v102
	v_mov_b32_e32 v94, v91
	v_lshlrev_b32_e32 v130, 16, v101
	v_mul_f32_e32 v84, v131, v131
	v_and_b32_e32 v105, 0xffff0000, v100
	v_lshlrev_b32_e32 v126, 16, v103
	v_mov_b32_e32 v127, v106
	v_pk_mul_f32 v[102:103], v[94:95], v[94:95]
	v_pk_fma_f32 v[196:197], v[130:131], v[130:131], v[84:85] op_sel_hi:[1,1,0]
	v_lshlrev_b32_e32 v104, 16, v100
	v_mul_f32_e32 v84, v105, v105
	v_and_b32_e32 v133, 0xffff0000, v99
	v_pk_fma_f32 v[194:195], v[126:127], v[126:127], v[102:103]
	v_pk_fma_f32 v[198:199], v[104:105], v[104:105], v[84:85] op_sel_hi:[1,1,0]
	v_lshlrev_b32_e32 v132, 16, v99
	v_mul_f32_e32 v84, v133, v133
	v_and_b32_e32 v103, 0xffff0000, v98
	v_pk_fma_f32 v[200:201], v[132:133], v[132:133], v[84:85] op_sel_hi:[1,1,0]
	v_lshlrev_b32_e32 v102, 16, v98
	v_mul_f32_e32 v84, v103, v103
	v_and_b32_e32 v135, 0xffff0000, v97
	v_pk_fma_f32 v[202:203], v[102:103], v[102:103], v[84:85] op_sel_hi:[1,1,0]
	v_lshlrev_b32_e32 v134, 16, v97
	v_mul_f32_e32 v84, v135, v135
	v_and_b32_e32 v101, 0xffff0000, v96
	v_pk_fma_f32 v[204:205], v[134:135], v[134:135], v[84:85] op_sel_hi:[1,1,0]
	v_lshlrev_b32_e32 v100, 16, v96
	v_mul_f32_e32 v84, v101, v101
	s_waitcnt vmcnt(0)
	v_and_b32_e32 v137, 0xffff0000, v143
	v_pk_fma_f32 v[206:207], v[100:101], v[100:101], v[84:85] op_sel_hi:[1,1,0]
	v_lshlrev_b32_e32 v136, 16, v143
	v_mul_f32_e32 v84, v137, v137
	v_and_b32_e32 v99, 0xffff0000, v142
	v_pk_fma_f32 v[208:209], v[136:137], v[136:137], v[84:85] op_sel_hi:[1,1,0]
	v_lshlrev_b32_e32 v98, 16, v142
	v_mul_f32_e32 v84, v99, v99
	v_and_b32_e32 v139, 0xffff0000, v141
	v_pk_fma_f32 v[210:211], v[98:99], v[98:99], v[84:85] op_sel_hi:[1,1,0]
	v_lshlrev_b32_e32 v138, 16, v141
	v_mul_f32_e32 v84, v139, v139
	v_and_b32_e32 v97, 0xffff0000, v140
	v_pk_fma_f32 v[212:213], v[138:139], v[138:139], v[84:85] op_sel_hi:[1,1,0]
	v_lshlrev_b32_e32 v96, 16, v140
	v_mul_f32_e32 v84, v97, v97
	v_and_b32_e32 v141, 0xffff0000, v151
	v_pk_fma_f32 v[214:215], v[96:97], v[96:97], v[84:85] op_sel_hi:[1,1,0]
	v_lshlrev_b32_e32 v140, 16, v151
	v_mul_f32_e32 v84, v141, v141
	v_and_b32_e32 v143, 0xffff0000, v150
	v_pk_fma_f32 v[216:217], v[140:141], v[140:141], v[84:85] op_sel_hi:[1,1,0]
	v_lshlrev_b32_e32 v142, 16, v150
	v_mul_f32_e32 v84, v143, v143
	v_and_b32_e32 v145, 0xffff0000, v149
	v_pk_fma_f32 v[218:219], v[142:143], v[142:143], v[84:85] op_sel_hi:[1,1,0]
	v_lshlrev_b32_e32 v144, 16, v149
	v_mul_f32_e32 v84, v145, v145
	v_and_b32_e32 v147, 0xffff0000, v148
	v_pk_fma_f32 v[220:221], v[144:145], v[144:145], v[84:85] op_sel_hi:[1,1,0]
	v_lshlrev_b32_e32 v146, 16, v148
	v_mul_f32_e32 v84, v147, v147
	v_and_b32_e32 v149, 0xffff0000, v167
	v_pk_fma_f32 v[222:223], v[146:147], v[146:147], v[84:85] op_sel_hi:[1,1,0]
	v_lshlrev_b32_e32 v148, 16, v167
	v_mul_f32_e32 v84, v149, v149
	v_and_b32_e32 v151, 0xffff0000, v166
	v_pk_fma_f32 v[224:225], v[148:149], v[148:149], v[84:85] op_sel_hi:[1,1,0]
	v_lshlrev_b32_e32 v150, 16, v166
	v_mul_f32_e32 v84, v151, v151
	v_and_b32_e32 v153, 0xffff0000, v165
	v_pk_fma_f32 v[226:227], v[150:151], v[150:151], v[84:85] op_sel_hi:[1,1,0]
	v_lshlrev_b32_e32 v152, 16, v165
	v_mul_f32_e32 v84, v153, v153
	v_and_b32_e32 v159, 0xffff0000, v164
	v_pk_fma_f32 v[228:229], v[152:153], v[152:153], v[84:85] op_sel_hi:[1,1,0]
	v_lshlrev_b32_e32 v158, 16, v164
	v_mul_f32_e32 v84, v159, v159
	v_and_b32_e32 v165, 0xffff0000, v175
	v_pk_fma_f32 v[230:231], v[158:159], v[158:159], v[84:85] op_sel_hi:[1,1,0]
	v_lshlrev_b32_e32 v164, 16, v175
	v_mul_f32_e32 v84, v165, v165
	v_and_b32_e32 v167, 0xffff0000, v174
	v_pk_fma_f32 v[232:233], v[164:165], v[164:165], v[84:85] op_sel_hi:[1,1,0]
	v_lshlrev_b32_e32 v166, 16, v174
	v_mul_f32_e32 v84, v167, v167
	v_and_b32_e32 v169, 0xffff0000, v173
	v_pk_fma_f32 v[234:235], v[166:167], v[166:167], v[84:85] op_sel_hi:[1,1,0]
	v_lshlrev_b32_e32 v168, 16, v173
	v_mul_f32_e32 v84, v169, v169
	v_and_b32_e32 v171, 0xffff0000, v172
	v_and_b32_e32 v175, 0xffff0000, v82
	v_pk_fma_f32 v[236:237], v[168:169], v[168:169], v[84:85] op_sel_hi:[1,1,0]
	v_lshlrev_b32_e32 v170, 16, v172
	v_mul_f32_e32 v84, v171, v171
	v_and_b32_e32 v173, 0xffff0000, v83
	v_lshlrev_b32_e32 v174, 16, v82
	v_mul_f32_e32 v82, v175, v175
	v_pk_fma_f32 v[238:239], v[170:171], v[170:171], v[84:85] op_sel_hi:[1,1,0]
	v_lshlrev_b32_e32 v172, 16, v83
	v_mul_f32_e32 v84, v173, v173
	v_pk_fma_f32 v[242:243], v[174:175], v[174:175], v[82:83] op_sel_hi:[1,1,0]
	v_and_b32_e32 v83, 0xffff0000, v81
	v_pk_fma_f32 v[240:241], v[172:173], v[172:173], v[84:85] op_sel_hi:[1,1,0]
	v_lshlrev_b32_e32 v82, 16, v81
	v_mul_f32_e32 v84, v83, v83
	v_lshlrev_b32_e32 v176, 16, v80
	v_mul_f32_e32 v80, v177, v177
	v_pk_fma_f32 v[244:245], v[82:83], v[82:83], v[84:85] op_sel_hi:[1,1,0]
	v_pk_fma_f32 v[80:81], v[176:177], v[176:177], v[80:81] op_sel_hi:[1,1,0]
	s_nop 0
	v_pk_add_f32 v[80:81], v[80:81], v[244:245]
	s_nop 0
	v_pk_add_f32 v[80:81], v[242:243], v[80:81]
	s_nop 0
	v_pk_add_f32 v[80:81], v[240:241], v[80:81]
	s_nop 0
	v_pk_add_f32 v[80:81], v[238:239], v[80:81]
	s_nop 0
	v_pk_add_f32 v[80:81], v[236:237], v[80:81]
	s_nop 0
	v_pk_add_f32 v[80:81], v[234:235], v[80:81]
	s_nop 0
	v_pk_add_f32 v[80:81], v[232:233], v[80:81]
	s_nop 0
	v_pk_add_f32 v[80:81], v[230:231], v[80:81]
	s_nop 0
	v_pk_add_f32 v[80:81], v[228:229], v[80:81]
	s_nop 0
	v_pk_add_f32 v[80:81], v[226:227], v[80:81]
	s_nop 0
	v_pk_add_f32 v[80:81], v[224:225], v[80:81]
	s_nop 0
	v_pk_add_f32 v[80:81], v[222:223], v[80:81]
	s_nop 0
	v_pk_add_f32 v[80:81], v[220:221], v[80:81]
	s_nop 0
	v_pk_add_f32 v[80:81], v[218:219], v[80:81]
	s_nop 0
	v_pk_add_f32 v[80:81], v[216:217], v[80:81]
	s_nop 0
	v_pk_add_f32 v[80:81], v[214:215], v[80:81]
	s_nop 0
	v_pk_add_f32 v[80:81], v[212:213], v[80:81]
	s_nop 0
	v_pk_add_f32 v[80:81], v[210:211], v[80:81]
	s_nop 0
	v_pk_add_f32 v[80:81], v[208:209], v[80:81]
	s_nop 0
	v_pk_add_f32 v[80:81], v[206:207], v[80:81]
	s_nop 0
	v_pk_add_f32 v[80:81], v[204:205], v[80:81]
	s_nop 0
	v_pk_add_f32 v[80:81], v[202:203], v[80:81]
	s_nop 0
	v_pk_add_f32 v[80:81], v[200:201], v[80:81]
	s_nop 0
	v_pk_add_f32 v[80:81], v[198:199], v[80:81]
	s_nop 0
	v_pk_add_f32 v[80:81], v[196:197], v[80:81]
	s_nop 0
	v_pk_add_f32 v[80:81], v[194:195], v[80:81] op_sel:[1,0] op_sel_hi:[0,1]
	v_pk_add_f32 v[80:81], v[194:195], v[80:81]
	s_nop 0
	v_pk_add_f32 v[80:81], v[192:193], v[80:81] op_sel:[1,0] op_sel_hi:[0,1]
	v_pk_add_f32 v[80:81], v[192:193], v[80:81]
	s_nop 0
	v_pk_add_f32 v[80:81], v[190:191], v[80:81] op_sel:[1,0] op_sel_hi:[0,1]
	v_pk_add_f32 v[80:81], v[190:191], v[80:81]
	s_nop 0
	v_mov_b32_e32 v81, v80
	s_nop 1
	v_permlane32_swap_b32_e32 v80, v81
	s_and_saveexec_b64 s[56:57], s[0:1]
	v_add_u32_e32 v84, 0, v187
	ds_write_b128 v84, v[112:115] offset:34816
	s_or_b64 exec, exec, s[56:57]
	v_add_f32_e32 v80, v80, v81
	v_fmamk_f32 v80, v80, 0x3c000000, v178
	v_mul_f32_e32 v81, 0x4b800000, v80
	v_cmp_gt_f32_e32 vcc, s68, v80
	v_mov_b32_e32 v123, v85
	v_mov_b32_e32 v109, v87
	v_cndmask_b32_e32 v80, v80, v81, vcc
	v_rsq_f32_e32 v80, v80
	v_mov_b32_e32 v111, v89
	v_mov_b32_e32 v127, v91
	v_mov_b32_e32 v125, v93
	v_mul_f32_e32 v81, 0x45800000, v80
	v_cndmask_b32_e32 v188, v80, v81, vcc
	v_pk_mul_f32 v[80:81], v[188:189], v[176:177] op_sel_hi:[0,1]
	s_waitcnt lgkmcnt(14)
	v_pk_mul_f32 v[76:77], v[76:77], v[80:81]
	v_mov_b32_e32 v107, v95
	v_cvt_pk_bf16_f32 v80, v76, v77
	v_pk_mul_f32 v[76:77], v[188:189], v[82:83] op_sel_hi:[0,1]
	v_pk_mul_f32 v[76:77], v[78:79], v[76:77]
	s_add_i32 s82, s3, s59
	v_cvt_pk_bf16_f32 v81, v76, v77
	v_pk_mul_f32 v[76:77], v[188:189], v[174:175] op_sel_hi:[0,1]
	v_pk_mul_f32 v[72:73], v[72:73], v[76:77]
	v_mul_lo_u32 v174, v119, s69
	v_cvt_pk_bf16_f32 v82, v72, v73
	v_pk_mul_f32 v[72:73], v[188:189], v[172:173] op_sel_hi:[0,1]
	v_pk_mul_f32 v[72:73], v[74:75], v[72:73]
	v_mul_lo_u32 v175, v189, s69
	v_cvt_pk_bf16_f32 v83, v72, v73
	v_pk_mul_f32 v[72:73], v[188:189], v[170:171] op_sel_hi:[0,1]
	s_waitcnt lgkmcnt(13)
	v_pk_mul_f32 v[68:69], v[68:69], v[72:73]
	s_add_i32 s15, s82, 16
	v_cvt_pk_bf16_f32 v84, v68, v69
	v_pk_mul_f32 v[68:69], v[188:189], v[168:169] op_sel_hi:[0,1]
	v_pk_mul_f32 v[68:69], v[70:71], v[68:69]
	v_lshlrev_b32_e32 v163, 3, v121
	v_cvt_pk_bf16_f32 v85, v68, v69
	v_pk_mul_f32 v[68:69], v[188:189], v[166:167] op_sel_hi:[0,1]
	s_waitcnt lgkmcnt(12)
	v_pk_mul_f32 v[64:65], v[64:65], v[68:69]
	s_add_i32 s82, s82, 47
	v_cvt_pk_bf16_f32 v86, v64, v65
	v_pk_mul_f32 v[64:65], v[188:189], v[164:165] op_sel_hi:[0,1]
	v_pk_mul_f32 v[64:65], v[66:67], v[64:65]
	s_mov_b32 s64, 1
	v_cvt_pk_bf16_f32 v87, v64, v65
	v_pk_mul_f32 v[64:65], v[188:189], v[158:159] op_sel_hi:[0,1]
	s_waitcnt lgkmcnt(11)
	v_pk_mul_f32 v[60:61], v[60:61], v[64:65]
	v_lshlrev_b32_e32 v159, 2, v121
	v_cvt_pk_bf16_f32 v88, v60, v61
	v_pk_mul_f32 v[60:61], v[188:189], v[152:153] op_sel_hi:[0,1]
	v_pk_mul_f32 v[60:61], v[62:63], v[60:61]
	v_add_u32_e32 v158, s15, v186
	v_cvt_pk_bf16_f32 v89, v60, v61
	v_pk_mul_f32 v[60:61], v[188:189], v[150:151] op_sel_hi:[0,1]
	s_waitcnt lgkmcnt(10)
	v_pk_mul_f32 v[56:57], v[56:57], v[60:61]
	v_mov_b32_e32 v60, v129
	v_cvt_pk_bf16_f32 v90, v56, v57
	v_pk_mul_f32 v[56:57], v[188:189], v[148:149] op_sel_hi:[0,1]
	v_pk_mul_f32 v[56:57], v[58:59], v[56:57]
	v_mov_b32_e32 v58, v129
	v_cvt_pk_bf16_f32 v91, v56, v57
	v_pk_mul_f32 v[56:57], v[188:189], v[146:147] op_sel_hi:[0,1]
	s_waitcnt lgkmcnt(9)
	v_pk_mul_f32 v[52:53], v[52:53], v[56:57]
	v_mov_b32_e32 v56, v129
	v_cvt_pk_bf16_f32 v92, v52, v53
	v_pk_mul_f32 v[52:53], v[188:189], v[144:145] op_sel_hi:[0,1]
	v_pk_mul_f32 v[52:53], v[54:55], v[52:53]
	v_mov_b32_e32 v54, v129
	v_cvt_pk_bf16_f32 v93, v52, v53
	v_pk_mul_f32 v[52:53], v[188:189], v[142:143] op_sel_hi:[0,1]
	s_waitcnt lgkmcnt(8)
	v_pk_mul_f32 v[48:49], v[48:49], v[52:53]
	v_mov_b32_e32 v52, v129
	v_cvt_pk_bf16_f32 v94, v48, v49
	v_pk_mul_f32 v[48:49], v[188:189], v[140:141] op_sel_hi:[0,1]
	v_pk_mul_f32 v[48:49], v[50:51], v[48:49]
	v_mov_b32_e32 v50, v129
	v_cvt_pk_bf16_f32 v95, v48, v49
	v_pk_mul_f32 v[48:49], v[188:189], v[96:97] op_sel_hi:[0,1]
	s_waitcnt lgkmcnt(7)
	v_pk_mul_f32 v[44:45], v[44:45], v[48:49]
	v_mov_b32_e32 v48, v129
	v_cvt_pk_bf16_f32 v96, v44, v45
	v_pk_mul_f32 v[44:45], v[188:189], v[138:139] op_sel_hi:[0,1]
	v_pk_mul_f32 v[44:45], v[46:47], v[44:45]
	v_mov_b32_e32 v49, v129
	v_cvt_pk_bf16_f32 v97, v44, v45
	v_pk_mul_f32 v[44:45], v[188:189], v[98:99] op_sel_hi:[0,1]
	s_waitcnt lgkmcnt(6)
	v_pk_mul_f32 v[40:41], v[40:41], v[44:45]
	v_mov_b32_e32 v51, v129
	v_cvt_pk_bf16_f32 v98, v40, v41
	v_pk_mul_f32 v[40:41], v[188:189], v[136:137] op_sel_hi:[0,1]
	v_pk_mul_f32 v[40:41], v[42:43], v[40:41]
	v_mov_b32_e32 v53, v129
	v_cvt_pk_bf16_f32 v99, v40, v41
	v_pk_mul_f32 v[40:41], v[188:189], v[100:101] op_sel_hi:[0,1]
	s_waitcnt lgkmcnt(5)
	v_pk_mul_f32 v[36:37], v[40:41], v[36:37]
	v_mov_b32_e32 v55, v129
	v_cvt_pk_bf16_f32 v100, v36, v37
	v_pk_mul_f32 v[36:37], v[188:189], v[134:135] op_sel_hi:[0,1]
	v_pk_mul_f32 v[36:37], v[36:37], v[38:39]
	v_mov_b32_e32 v57, v129
	v_cvt_pk_bf16_f32 v101, v36, v37
	v_pk_mul_f32 v[36:37], v[188:189], v[102:103] op_sel_hi:[0,1]
	s_waitcnt lgkmcnt(4)
	v_pk_mul_f32 v[32:33], v[36:37], v[32:33]
	v_mov_b32_e32 v59, v129
	v_cvt_pk_bf16_f32 v102, v32, v33
	v_pk_mul_f32 v[32:33], v[188:189], v[132:133] op_sel_hi:[0,1]
	v_pk_mul_f32 v[32:33], v[32:33], v[34:35]
	v_mov_b32_e32 v61, v129
	v_cvt_pk_bf16_f32 v103, v32, v33
	v_pk_mul_f32 v[32:33], v[188:189], v[104:105] op_sel_hi:[0,1]
	s_waitcnt lgkmcnt(3)
	v_pk_mul_f32 v[28:29], v[32:33], v[28:29]
	v_mov_b32_e32 v62, v129
	v_cvt_pk_bf16_f32 v104, v28, v29
	v_pk_mul_f32 v[28:29], v[188:189], v[130:131] op_sel_hi:[0,1]
	v_pk_mul_f32 v[28:29], v[28:29], v[30:31]
	v_mov_b32_e32 v63, v129
	v_cvt_pk_bf16_f32 v105, v28, v29
	v_pk_mul_f32 v[28:29], v[188:189], v[106:107] op_sel_hi:[0,1]
	s_waitcnt lgkmcnt(2)
	v_pk_mul_f32 v[24:25], v[28:29], v[24:25]
	v_mov_b64_e32 v[32:33], v[48:49]
	v_cvt_pk_bf16_f32 v106, v24, v25
	v_pk_mul_f32 v[24:25], v[188:189], v[126:127] op_sel_hi:[0,1]
	v_pk_mul_f32 v[24:25], v[24:25], v[26:27]
	v_mul_u32_u24_e32 v169, 0x110, v186
	v_cvt_pk_bf16_f32 v107, v24, v25
	v_pk_mul_f32 v[24:25], v[188:189], v[108:109] op_sel_hi:[0,1]
	s_waitcnt lgkmcnt(1)
	v_pk_mul_f32 v[20:21], v[24:25], v[20:21]
	v_mov_b32_e32 v155, v158
	v_cvt_pk_bf16_f32 v108, v20, v21
	v_pk_mul_f32 v[20:21], v[188:189], v[124:125] op_sel_hi:[0,1]
	v_pk_mul_f32 v[20:21], v[20:21], v[22:23]
	v_lshl_add_u64 v[164:165], v[116:117], 2, s[4:5]
	v_cvt_pk_bf16_f32 v109, v20, v21
	v_pk_mul_f32 v[20:21], v[188:189], v[110:111] op_sel_hi:[0,1]
	s_waitcnt lgkmcnt(0)
	v_pk_mul_f32 v[16:17], v[20:21], v[16:17]
	v_add_u32_e32 v20, 0, v128
	v_cvt_pk_bf16_f32 v110, v16, v17
	v_pk_mul_f32 v[16:17], v[188:189], v[122:123] op_sel_hi:[0,1]
	v_pk_mul_f32 v[16:17], v[16:17], v[18:19]
	v_and_b32_e32 v19, 16, v154
	v_cvt_pk_bf16_f32 v111, v16, v17
	v_lshlrev_b32_e32 v16, 16, v12
	v_and_b32_e32 v17, 0xffff0000, v12
	v_pk_mul_f32 v[16:17], v[120:121], v[16:17] op_sel_hi:[0,1]
	v_cvt_pk_bf16_f32 v12, v16, v17
	v_lshlrev_b32_e32 v16, 16, v13
	v_and_b32_e32 v17, 0xffff0000, v13
	v_pk_mul_f32 v[16:17], v[120:121], v[16:17] op_sel_hi:[0,1]
	v_cvt_pk_bf16_f32 v13, v16, v17
	v_lshlrev_b32_e32 v16, 16, v14
	v_and_b32_e32 v17, 0xffff0000, v14
	v_pk_mul_f32 v[16:17], v[120:121], v[16:17] op_sel_hi:[0,1]
	v_cvt_pk_bf16_f32 v14, v16, v17
	v_lshlrev_b32_e32 v16, 16, v15
	v_and_b32_e32 v17, 0xffff0000, v15
	v_pk_mul_f32 v[16:17], v[120:121], v[16:17] op_sel_hi:[0,1]
	v_cvt_pk_bf16_f32 v15, v16, v17
	v_add_u32_e32 v16, v20, v174
	ds_write_b128 v16, v[12:15]
	ds_write_b128 v248, v[8:11] offset:17408
	v_lshlrev_b32_e32 v8, 16, v4
	v_and_b32_e32 v9, 0xffff0000, v4
	v_pk_mul_f32 v[8:9], v[118:119], v[8:9] op_sel_hi:[0,1]
	v_cvt_pk_bf16_f32 v4, v8, v9
	v_lshlrev_b32_e32 v8, 16, v5
	v_and_b32_e32 v9, 0xffff0000, v5
	v_pk_mul_f32 v[8:9], v[118:119], v[8:9] op_sel_hi:[0,1]
	v_cvt_pk_bf16_f32 v5, v8, v9
	v_lshlrev_b32_e32 v8, 16, v6
	v_and_b32_e32 v9, 0xffff0000, v6
	v_pk_mul_f32 v[8:9], v[118:119], v[8:9] op_sel_hi:[0,1]
	v_cvt_pk_bf16_f32 v6, v8, v9
	v_lshlrev_b32_e32 v8, 16, v7
	v_and_b32_e32 v9, 0xffff0000, v7
	v_pk_mul_f32 v[8:9], v[118:119], v[8:9] op_sel_hi:[0,1]
	v_cvt_pk_bf16_f32 v7, v8, v9
	v_add_u32_e32 v8, v20, v175
	ds_write_b128 v8, v[4:7]
	ds_write_b128 v248, v[0:3] offset:25600
	v_lshlrev_b32_e32 v1, 2, v185
	v_lshrrev_b32_e32 v18, 2, v154
	v_and_or_b32 v1, v1, 12, v19
	v_and_or_b32 v0, v18, 3, v159
	v_lshlrev_b32_e32 v177, 1, v1
	v_or_b32_e32 v1, 32, v185
	v_mul_u32_u24_e32 v176, 0x110, v1
	v_mul_u32_u24_e32 v188, 0x110, v0
	v_mov_b64_e32 v[16:17], v[48:49]
	v_mov_b64_e32 v[0:1], v[48:49]
	s_and_b32 s12, s58, 0xfc0
	v_subrev_u32_e32 v189, 64, v189
	v_subrev_u32_e32 v190, 64, v119
	v_mov_b32_e32 v167, 0
	v_mov_b32_e32 v192, 0xff800000
	v_mov_b64_e32 v[34:35], v[50:51]
	v_mov_b64_e32 v[36:37], v[52:53]
	v_mov_b64_e32 v[38:39], v[54:55]
	v_mov_b64_e32 v[40:41], v[56:57]
	v_mov_b64_e32 v[42:43], v[58:59]
	v_mov_b64_e32 v[44:45], v[60:61]
	v_mov_b64_e32 v[46:47], v[62:63]
	v_mov_b64_e32 v[18:19], v[50:51]
	v_mov_b64_e32 v[20:21], v[52:53]
	v_mov_b64_e32 v[22:23], v[54:55]
	v_mov_b64_e32 v[24:25], v[56:57]
	v_mov_b64_e32 v[26:27], v[58:59]
	v_mov_b64_e32 v[28:29], v[60:61]
	v_mov_b64_e32 v[30:31], v[62:63]
	v_mov_b64_e32 v[2:3], v[50:51]
	v_mov_b64_e32 v[4:5], v[52:53]
	v_mov_b64_e32 v[6:7], v[54:55]
	v_mov_b64_e32 v[8:9], v[56:57]
	v_mov_b64_e32 v[10:11], v[58:59]
	v_mov_b64_e32 v[12:13], v[60:61]
	v_mov_b64_e32 v[14:15], v[62:63]
	v_lshl_add_u64 v[138:139], s[12:13], 2, v[164:165]
	v_add_u32_e32 v65, s12, v190
	v_mov_b32_e32 v140, s33
	v_cmp_lt_i32_e32 vcc, 15, v65
	v_min_i32_e32 v64, 0x80f, v65
	s_nop 0
	v_cndmask_b32_e32 v65, v179, v140, vcc
	v_add_u32_e32 v66, v65, v64
	v_ashrrev_i32_e32 v67, 31, v66
	v_lshlrev_b64 v[66:67], 14, v[66:67]
	v_lshl_add_u64 v[66:67], v[160:161], 0, v[66:67]
	v_add_co_u32_e32 v72, vcc, s65, v66
	v_ashrrev_i32_e32 v65, 31, v64
	s_nop 0
	v_addc_co_u32_e32 v73, vcc, 0, v67, vcc
	v_add_co_u32_e32 v74, vcc, s63, v66
	v_lshl_add_u64 v[134:135], v[64:65], 2, s[54:55]
	s_nop 0
	v_addc_co_u32_e32 v75, vcc, 0, v67, vcc
	v_add_u32_e32 v67, s12, v189
	v_cmp_lt_i32_e32 vcc, 15, v67
	v_min_i32_e32 v66, 0x80f, v67
	s_nop 0
	v_cndmask_b32_e32 v67, v179, v140, vcc
	v_add_u32_e32 v68, v67, v66
	v_ashrrev_i32_e32 v69, 31, v68
	v_lshlrev_b64 v[68:69], 14, v[68:69]
	v_lshl_add_u64 v[68:69], v[160:161], 0, v[68:69]
	v_add_co_u32_e32 v76, vcc, 0x2000, v68
	v_ashrrev_i32_e32 v67, 31, v66
	s_nop 0
	v_addc_co_u32_e32 v77, vcc, 0, v69, vcc
	v_add_co_u32_e32 v78, vcc, 0x3000, v68
	v_lshl_add_u64 v[136:137], v[66:67], 2, s[54:55]
	s_nop 0
	v_addc_co_u32_e32 v79, vcc, 0, v69, vcc
	s_and_saveexec_b64 s[4:5], s[0:1]
	s_cbranch_execz .Llde_p
	global_load_dwordx4 v[112:115], v[138:139], off offset:-256
